# workgroups 0..63 leave the mixer-in grid barrier as soon as they have arrived and the norm counter of the h block they read is complete (their gMLP column-tile GEMM reads no mixer-in output)
# speedup vs baseline: 1.0204x; 1.0027x over previous
.LBB0_939:
	s_or_b64 exec, exec, s[12:13]
	v_cvt_f32_u32_e32 v4, v2
	s_waitcnt vmcnt(0)
	v_readfirstlane_b32 s2, v3
	v_sub_u32_e32 v3, 0, v2
	v_rcp_iflag_f32_e32 v4, v4
	v_add_u32_e32 v5, s2, v1
	v_mul_f32_e32 v4, 0x4f7ffffe, v4
	v_cvt_u32_f32_e32 v4, v4
	v_mul_lo_u32 v1, v3, v4
	v_mul_hi_u32 v1, v4, v1
	v_add_u32_e32 v1, v4, v1
	v_mul_hi_u32 v1, v5, v1
	v_mul_lo_u32 v3, v1, v2
	v_sub_u32_e32 v3, v5, v3
	v_add_u32_e32 v4, 1, v1
	v_cmp_ge_u32_e32 vcc, v3, v2
	s_nop 1
	v_cndmask_b32_e32 v1, v1, v4, vcc
	v_sub_u32_e32 v4, v3, v2
	v_cndmask_b32_e32 v3, v3, v4, vcc
	v_add_u32_e32 v4, 1, v1
	v_cmp_ge_u32_e32 vcc, v3, v2
	v_add_u32_e32 v3, 1, v5
	s_nop 0
	v_cndmask_b32_e32 v1, v1, v4, vcc
	v_mul_lo_u32 v4, v2, v1
	v_add_u32_e32 v2, v4, v2
	v_cmp_ne_u32_e32 vcc, v3, v2
	s_and_saveexec_b64 s[10:11], vcc
	s_xor_b64 s[10:11], exec, s[10:11]
	s_cbranch_execz .LBB0_953
	v_readlane_b32 s18, v255, 0
	s_nop 0
	s_cmp_lt_u32 s18, 64
	s_cbranch_scc0 .Lb5_std
	s_and_b32 s18, s18, 31
	s_lshl_b32 s18, s18, 7
	s_add_u32 s18, s18, 0xb000
	v_readlane_b32 s19, v255, 47
	v_mov_b32_e32 v0, s18
	s_mov_b32 s2, 0
	s_waitcnt lgkmcnt(0)
.Lb5_poll:
	global_load_dword v2, v0, s[6:7] sc1
	s_waitcnt vmcnt(0)
	v_readfirstlane_b32 s18, v2
	s_nop 0
	s_cmp_ge_u32 s18, s19
	s_cbranch_scc1 .Lb5_join
	s_sleep 1
	s_add_u32 s2, s2, 1
	s_cmp_lt_u32 s2, 0x2000
	s_cbranch_scc1 .Lb5_poll
	s_branch .Lb5_join
.Lb5_std:
	s_waitcnt lgkmcnt(0)
	global_load_dword v0, v186, s[8:9] offset:1024 sc1
	s_add_u32 s18, s8, 0x2400
	s_addc_u32 s19, s9, 0
	s_waitcnt vmcnt(0)
	v_cmp_eq_u32_e32 vcc, v0, v1
	s_and_saveexec_b64 s[12:13], vcc
	s_cbranch_execz .LBB0_952
	s_add_u32 s14, s6, 0x4200
	s_addc_u32 s15, s7, 0
	s_mov_b32 s2, 1
	s_mov_b64 s[20:21], 0
	s_branch .LBB0_943

.Lb5_join:
	s_waitcnt vmcnt(0)
	s_waitcnt vmcnt(0)
